# ph0 S5 tables: BB loads batched (8 dwordx4 up front) instead of 16 serial load-wait-store trips; tables on WGs 248-255
# speedup vs baseline: 1.0132x; 1.0132x over previous
.LBB0_689:
	s_add_i32 s0, s52, 0xffffff08
	s_cmpk_eq_i32 s33, 0x100
	s_cselect_b32 s0, s0, s52
	v_lshl_add_u32 v12, s0, 9, v84
	v_cmp_gt_u32_e32 vcc, s66, v12
	s_and_saveexec_b64 s[4:5], vcc
	s_cbranch_execz .LBB0_692
	v_readlane_b32 s0, v253, 52
	v_ashrrev_i32_e32 v13, 31, v12
	v_lshlrev_b64 v[18:19], 6, v[12:13]
	v_mov_b32_e32 v0, s0
	v_readlane_b32 s0, v253, 53
	v_lshlrev_b64 v[16:17], 7, v[12:13]
	v_or_b32_e32 v18, 60, v18
	v_mov_b32_e32 v4, s0
	v_readlane_b32 s0, v253, 54
	ds_read2_b64 v[0:3], v0 offset1:1
	ds_read2_b64 v[4:7], v4 offset1:1
	v_mov_b32_e32 v8, s0
	ds_read_b64 v[14:15], v8
	v_lshlrev_b64 v[20:21], 2, v[12:13]
	v_mad_i64_i32 v[22:23], s[0:1], v12, s65, 0
	s_mov_b64 s[6:7], 0
.LBB0_691:
	v_lshrrev_b32_e32 v13, 6, v12
	s_waitcnt lgkmcnt(2)
	v_readfirstlane_b32 s1, v1
	v_readfirstlane_b32 s0, v0
	v_ashrrev_i32_e32 v24, 6, v12
	s_waitcnt lgkmcnt(1)
	v_readfirstlane_b32 s10, v5
	v_readfirstlane_b32 s11, v4
	v_lshl_add_u64 v[8:9], s[78:79], 0, v[22:23]
	v_lshl_add_u64 v[10:11], s[0:1], 0, v[20:21]
	v_bfi_b32 v34, -16, v24, v13
	s_mov_b32 s0, 0xdc00000
	v_readfirstlane_b32 s9, v3
	v_readfirstlane_b32 s8, v2
	v_mov_b32_e32 v32, s11
	v_mov_b32_e32 v33, s10
	v_add_co_u32_e32 v30, vcc, s0, v8
	v_ashrrev_i32_e32 v35, 31, v34
	v_lshl_add_u64 v[28:29], s[8:9], 0, v[20:21]
	v_addc_co_u32_e32 v31, vcc, 0, v9, vcc
	v_lshl_add_u64 v[8:9], v[34:35], 2, v[32:33]
	global_load_dword v10, v[10:11], off
	s_nop 0
	global_load_dword v29, v[28:29], off
	s_waitcnt lgkmcnt(0)
	v_readfirstlane_b32 s15, v15
	global_load_dword v8, v[8:9], off
	v_readfirstlane_b32 s14, v14
	v_readfirstlane_b32 s13, v7
	v_readfirstlane_b32 s12, v6
	v_lshl_add_u64 v[26:27], s[14:15], 0, v[18:19]
	s_mov_b32 s0, 0xdd00000
	v_lshl_add_u64 v[24:25], s[12:13], 0, v[18:19]
	v_add_u32_e32 v12, s18, v12
	v_lshl_add_u64 v[22:23], v[22:23], 0, s[20:21]
	v_lshl_add_u64 v[18:19], v[18:19], 0, s[28:29]
	v_lshl_add_u64 v[20:21], v[20:21], 0, s[30:31]
	s_waitcnt vmcnt(2)
	v_max_f32_e32 v9, v10, v10
	v_min_f32_e32 v28, 0xb8d1b717, v9
	s_waitcnt vmcnt(1)
	v_mul_f32_e32 v10, 0, v29
	s_waitcnt vmcnt(0)
	v_mul_f32_e32 v8, 0x3fb8aa3b, v8
	v_exp_f32_e32 v8, v8
	v_mul_f32_e32 v9, 0, v28
	v_add_f32_e32 v11, v29, v29
	v_mul_f32_e32 v13, 0x40400000, v29
	v_mul_f32_e32 v32, 4.0, v29
	v_mul_f32_e32 v33, 0x40a00000, v29
	v_mul_f32_e32 v34, 0x40c00000, v29
	v_mul_f32_e32 v35, 0x40e00000, v29
	v_mul_f32_e32 v36, 0x41000000, v29
	v_mul_f32_e32 v37, 0x41100000, v29
	v_mul_f32_e32 v38, 0x41200000, v29
	v_mul_f32_e32 v39, 0x41300000, v29
	v_mul_f32_e32 v40, 0x41400000, v29
	v_mul_f32_e32 v41, 0x41500000, v29
	v_mul_f32_e32 v42, 0x41600000, v29
	v_mul_f32_e32 v43, 0x41700000, v29
	v_mul_f32_e32 v44, 0x41800000, v29
	v_add_f32_e32 v45, v28, v28
	v_mul_f32_e32 v46, 0x40400000, v28
	v_mul_f32_e32 v47, 4.0, v28
	v_mul_f32_e32 v48, 0x40a00000, v28
	v_mul_f32_e32 v49, 0x40c00000, v28
	v_mul_f32_e32 v50, 0x40e00000, v28
	v_mul_f32_e32 v51, 0x41000000, v28
	v_mul_f32_e32 v52, 0x41100000, v28
	v_mul_f32_e32 v53, 0x41200000, v28
	v_mul_f32_e32 v54, 0x41300000, v28
	v_mul_f32_e32 v55, 0x41400000, v28
	v_mul_f32_e32 v56, 0x41500000, v28
	v_mul_f32_e32 v57, 0x41600000, v28
	v_mul_f32_e32 v58, 0x41700000, v28
	v_mul_f32_e32 v59, 0x41800000, v28
	v_mul_f32_e32 v9, v9, v8
	v_mul_f32_e32 v60, v10, v8
	v_mul_f32_e32 v61, v29, v8
	v_mul_f32_e32 v10, v28, v8
	v_mul_f32_e32 v45, v45, v8
	v_mul_f32_e32 v11, v11, v8
	v_mul_f32_e32 v46, v46, v8
	v_mul_f32_e32 v13, v13, v8
	v_mul_f32_e32 v47, v47, v8
	v_mul_f32_e32 v62, v32, v8
	v_mul_f32_e32 v32, v48, v8
	v_mul_f32_e32 v33, v33, v8
	v_mul_f32_e32 v48, v49, v8
	v_mul_f32_e32 v49, v34, v8
	v_mul_f32_e32 v34, v50, v8
	v_mul_f32_e32 v35, v35, v8
	v_mul_f32_e32 v50, v51, v8
	v_mul_f32_e32 v51, v36, v8
	v_mul_f32_e32 v36, v52, v8
	v_mul_f32_e32 v37, v37, v8
	v_mul_f32_e32 v52, v53, v8
	v_mul_f32_e32 v53, v38, v8
	v_mul_f32_e32 v38, v54, v8
	v_mul_f32_e32 v39, v39, v8
	v_mul_f32_e32 v54, v55, v8
	v_mul_f32_e32 v55, v40, v8
	v_mul_f32_e32 v40, v56, v8
	v_mul_f32_e32 v41, v41, v8
	v_mul_f32_e32 v56, v57, v8
	v_mul_f32_e32 v57, v42, v8
	v_mul_f32_e32 v42, v58, v8
	v_mul_f32_e32 v43, v43, v8
	v_mul_f32_e32 v58, v59, v8
	v_mul_f32_e32 v59, v44, v8
	v_mul_f32_e32 v8, 0x3fb8aa3b, v9
	v_mul_f32_e32 v9, 0.15915494, v60
	v_mul_f32_e32 v44, 0.15915494, v61
	v_floor_f32_e32 v9, v9
	v_floor_f32_e32 v86, v44
	v_mul_f32_e32 v10, 0x3fb8aa3b, v10
	v_fma_f32 v9, v60, 0.15915494, -v9
	v_fma_f32 v61, v61, 0.15915494, -v86
	v_exp_f32_e32 v8, v8
	v_exp_f32_e32 v10, v10
	v_cos_f32_e32 v86, v9
	v_sin_f32_e32 v87, v9
	v_cos_f32_e32 v88, v61
	v_sin_f32_e32 v89, v61
	v_mul_f32_e32 v45, 0x3fb8aa3b, v45
	v_mul_f32_e32 v63, 0.15915494, v11
	v_mul_f32_e32 v46, 0x3fb8aa3b, v46
	v_mul_f32_e32 v64, 0.15915494, v13
	v_mul_f32_e32 v47, 0x3fb8aa3b, v47
	v_mul_f32_e32 v65, 0.15915494, v62
	v_mul_f32_e32 v66, 0x3fb8aa3b, v32
	v_mul_f32_e32 v67, 0.15915494, v33
	v_mul_f32_e32 v68, 0.15915494, v49
	v_mul_f32_e32 v69, 0x3fb8aa3b, v34
	v_mul_f32_e32 v70, 0.15915494, v35
	v_mul_f32_e32 v71, 0.15915494, v51
	v_mul_f32_e32 v72, 0x3fb8aa3b, v36
	v_mul_f32_e32 v73, 0.15915494, v37
	v_mul_f32_e32 v74, 0.15915494, v53
	v_mul_f32_e32 v76, 0.15915494, v39
	v_mul_f32_e32 v77, 0.15915494, v55
	v_mul_f32_e32 v79, 0.15915494, v41
	v_mul_f32_e32 v80, 0.15915494, v57
	v_mul_f32_e32 v81, 0.15915494, v43
	v_mul_f32_e32 v85, 0x3fb8aa3b, v58
	v_mul_f32_e32 v58, 0.15915494, v59
	v_mul_f32_e32 v75, 0x3fb8aa3b, v38
	v_mul_f32_e32 v82, 0x3fb8aa3b, v42
	v_exp_f32_e32 v32, v45
	v_floor_f32_e32 v45, v63
	v_exp_f32_e32 v34, v46
	v_floor_f32_e32 v63, v64
	v_exp_f32_e32 v36, v47
	v_floor_f32_e32 v47, v65
	v_exp_f32_e32 v38, v66
	v_floor_f32_e32 v64, v67
	v_floor_f32_e32 v65, v68
	v_exp_f32_e32 v42, v69
	v_floor_f32_e32 v66, v70
	v_floor_f32_e32 v67, v71
	v_exp_f32_e32 v46, v72
	v_floor_f32_e32 v68, v73
	v_floor_f32_e32 v69, v74
	v_floor_f32_e32 v70, v76
	v_floor_f32_e32 v71, v77
	v_floor_f32_e32 v60, v79
	v_floor_f32_e32 v72, v80
	v_floor_f32_e32 v73, v81
	v_floor_f32_e32 v58, v58
	v_mul_f32_e32 v48, 0x3fb8aa3b, v48
	v_mul_f32_e32 v50, 0x3fb8aa3b, v50
	v_mul_f32_e32 v52, 0x3fb8aa3b, v52
	v_mul_f32_e32 v54, 0x3fb8aa3b, v54
	v_mul_f32_e32 v78, 0x3fb8aa3b, v40
	v_mul_f32_e32 v56, 0x3fb8aa3b, v56
	v_fma_f32 v11, v11, 0.15915494, -v45
	v_fma_f32 v13, v13, 0.15915494, -v63
	v_fma_f32 v45, v62, 0.15915494, -v47
	v_fma_f32 v33, v33, 0.15915494, -v64
	v_fma_f32 v47, v49, 0.15915494, -v65
	v_fma_f32 v35, v35, 0.15915494, -v66
	v_fma_f32 v49, v51, 0.15915494, -v67
	v_fma_f32 v37, v37, 0.15915494, -v68
	v_fma_f32 v51, v53, 0.15915494, -v69
	v_fma_f32 v39, v39, 0.15915494, -v70
	v_fma_f32 v53, v55, 0.15915494, -v71
	v_fma_f32 v41, v41, 0.15915494, -v60
	v_fma_f32 v55, v57, 0.15915494, -v72
	v_fma_f32 v43, v43, 0.15915494, -v73
	v_fma_f32 v57, v59, 0.15915494, -v58
	v_exp_f32_e32 v40, v48
	v_exp_f32_e32 v44, v50
	v_exp_f32_e32 v48, v52
	v_exp_f32_e32 v50, v75
	v_exp_f32_e32 v52, v54
	v_exp_f32_e32 v54, v78
	v_exp_f32_e32 v56, v56
	v_cos_f32_e32 v58, v11
	v_sin_f32_e32 v59, v11
	v_cos_f32_e32 v60, v13
	v_sin_f32_e32 v61, v13
	v_cos_f32_e32 v62, v45
	v_sin_f32_e32 v63, v45
	v_cos_f32_e32 v64, v33
	v_sin_f32_e32 v65, v33
	v_cos_f32_e32 v66, v47
	v_sin_f32_e32 v67, v47
	v_cos_f32_e32 v68, v35
	v_sin_f32_e32 v69, v35
	v_cos_f32_e32 v70, v49
	v_sin_f32_e32 v71, v49
	v_cos_f32_e32 v72, v37
	v_sin_f32_e32 v73, v37
	v_cos_f32_e32 v74, v51
	v_sin_f32_e32 v75, v51
	v_cos_f32_e32 v76, v39
	v_sin_f32_e32 v77, v39
	v_cos_f32_e32 v78, v53
	v_sin_f32_e32 v79, v53
	v_cos_f32_e32 v80, v41
	v_sin_f32_e32 v81, v41
	v_exp_f32_e32 v82, v82
	v_pk_mul_f32 v[8:9], v[8:9], v[86:87] op_sel_hi:[0,1]
	v_pk_mul_f32 v[10:11], v[10:11], v[88:89] op_sel_hi:[0,1]
	v_cos_f32_e32 v86, v55
	v_sin_f32_e32 v87, v55
	v_cos_f32_e32 v88, v43
	v_sin_f32_e32 v89, v43
	v_cos_f32_e32 v90, v57
	v_sin_f32_e32 v91, v57
	v_exp_f32_e32 v92, v85
	v_pk_mul_f32 v[32:33], v[32:33], v[58:59] op_sel_hi:[0,1]
	v_pk_mul_f32 v[34:35], v[34:35], v[60:61] op_sel_hi:[0,1]
	v_pk_mul_f32 v[36:37], v[36:37], v[62:63] op_sel_hi:[0,1]
	v_pk_mul_f32 v[38:39], v[38:39], v[64:65] op_sel_hi:[0,1]
	v_pk_mul_f32 v[40:41], v[40:41], v[66:67] op_sel_hi:[0,1]
	v_pk_mul_f32 v[42:43], v[42:43], v[68:69] op_sel_hi:[0,1]
	v_pk_mul_f32 v[44:45], v[44:45], v[70:71] op_sel_hi:[0,1]
	v_pk_mul_f32 v[46:47], v[46:47], v[72:73] op_sel_hi:[0,1]
	v_pk_mul_f32 v[48:49], v[48:49], v[74:75] op_sel_hi:[0,1]
	v_pk_mul_f32 v[50:51], v[50:51], v[76:77] op_sel_hi:[0,1]
	v_pk_mul_f32 v[52:53], v[52:53], v[78:79] op_sel_hi:[0,1]
	v_pk_mul_f32 v[54:55], v[54:55], v[80:81] op_sel_hi:[0,1]
	v_pk_mul_f32 v[56:57], v[56:57], v[86:87] op_sel_hi:[0,1]
	v_pk_mul_f32 v[58:59], v[82:83], v[88:89] op_sel_hi:[0,1]
	v_pk_mul_f32 v[60:61], v[92:93], v[90:91] op_sel_hi:[0,1]
	global_store_dwordx4 v[30:31], v[8:11], off
	global_store_dwordx4 v[30:31], v[32:35], off offset:16
	global_store_dwordx4 v[30:31], v[36:39], off offset:32
	global_store_dwordx4 v[30:31], v[40:43], off offset:48
	global_store_dwordx4 v[30:31], v[44:47], off offset:64
	global_store_dwordx4 v[30:31], v[48:51], off offset:80
	global_store_dwordx4 v[30:31], v[52:55], off offset:96
	global_store_dwordx4 v[30:31], v[56:59], off offset:112
	global_store_dwordx2 v[30:31], v[60:61], off offset:128
	global_load_dwordx4 v[44:47], v[26:27], off offset:-60
	global_load_dwordx4 v[48:51], v[26:27], off offset:-44
	global_load_dwordx4 v[52:55], v[26:27], off offset:-28
	global_load_dwordx4 v[56:59], v[26:27], off offset:-12
	global_load_dwordx4 v[60:63], v[24:25], off offset:-60
	global_load_dwordx4 v[64:67], v[24:25], off offset:-44
	global_load_dwordx4 v[68:71], v[24:25], off offset:-28
	global_load_dwordx4 v[72:75], v[24:25], off offset:-12
	v_add_f32_e32 v38, -1.0, v10
	v_mov_b32_e32 v39, v11
	v_mov_b32_e32 v34, v29
	v_pk_mov_b32 v[10:11], v[10:11], v[38:39] op_sel:[1,0]
	v_pk_mul_f32 v[36:37], v[28:29], v[28:29]
	v_pk_mul_f32 v[10:11], v[34:35], v[10:11] op_sel_hi:[0,1]
	v_lshl_add_u64 v[32:33], s[78:79], 0, v[16:17]
	v_pk_add_f32 v[36:37], v[36:37], v[36:37] op_sel:[0,1] op_sel_hi:[0,1]
	v_pk_fma_f32 v[34:35], v[28:29], v[38:39], v[10:11]
	v_pk_fma_f32 v[10:11], v[28:29], v[38:39], v[10:11] op_sel_hi:[0,1,1] neg_lo:[0,0,1] neg_hi:[0,0,1]
	v_add_co_u32_e32 v32, vcc, s0, v32
	v_div_scale_f32 v9, s[0:1], v37, v37, v11
	v_div_scale_f32 v13, s[0:1], v36, v36, v34
	v_rcp_f32_e32 v29, v9
	v_rcp_f32_e32 v31, v13
	v_addc_co_u32_e32 v33, vcc, 0, v33, vcc
	v_fma_f32 v35, -v9, v29, 1.0
	v_div_scale_f32 v10, vcc, v11, v37, v11
	v_fma_f32 v38, -v13, v31, 1.0
	v_fmac_f32_e32 v29, v35, v29
	v_div_scale_f32 v28, s[0:1], v34, v36, v34
	v_fmac_f32_e32 v31, v38, v31
	v_mul_f32_e32 v35, v10, v29
	v_mul_f32_e32 v38, v28, v31
	v_fma_f32 v39, -v9, v35, v10
	v_fma_f32 v40, -v13, v38, v28
	v_fmac_f32_e32 v35, v39, v29
	v_fmac_f32_e32 v38, v40, v31
	v_fma_f32 v9, -v9, v35, v10
	v_fma_f32 v10, -v13, v38, v28
	v_div_fmas_f32 v9, v9, v29, v35
	s_mov_b64 vcc, s[0:1]
	v_div_fixup_f32 v11, v9, v37, v11
	v_div_fmas_f32 v9, v10, v31, v38
	v_div_fixup_f32 v10, v9, v36, v34
	s_movk_i32 s0, 0xfff
	v_cmp_lt_i32_e32 vcc, s0, v12
	v_lshl_add_u64 v[16:17], v[16:17], 0, s[24:25]
	s_or_b64 s[6:7], vcc, s[6:7]
	s_waitcnt vmcnt(0)
	v_mul_f32_e32 v86, v11, v44
	v_mul_f32_e32 v87, v10, v44
	v_fma_f32 v86, v10, v60, -v86
	v_fma_f32 v87, v11, v60, v87
	global_store_dwordx2 v[32:33], v[86:87], off offset:0
	v_mul_f32_e32 v88, v11, v45
	v_mul_f32_e32 v89, v10, v45
	v_fma_f32 v88, v10, v61, -v88
	v_fma_f32 v89, v11, v61, v89
	global_store_dwordx2 v[32:33], v[88:89], off offset:8
	v_mul_f32_e32 v90, v11, v46
	v_mul_f32_e32 v91, v10, v46
	v_fma_f32 v90, v10, v62, -v90
	v_fma_f32 v91, v11, v62, v91
	global_store_dwordx2 v[32:33], v[90:91], off offset:16
	v_mul_f32_e32 v92, v11, v47
	v_mul_f32_e32 v93, v10, v47
	v_fma_f32 v92, v10, v63, -v92
	v_fma_f32 v93, v11, v63, v93
	global_store_dwordx2 v[32:33], v[92:93], off offset:24
	v_mul_f32_e32 v86, v11, v48
	v_mul_f32_e32 v87, v10, v48
	v_fma_f32 v86, v10, v64, -v86
	v_fma_f32 v87, v11, v64, v87
	global_store_dwordx2 v[32:33], v[86:87], off offset:32
	v_mul_f32_e32 v88, v11, v49
	v_mul_f32_e32 v89, v10, v49
	v_fma_f32 v88, v10, v65, -v88
	v_fma_f32 v89, v11, v65, v89
	global_store_dwordx2 v[32:33], v[88:89], off offset:40
	v_mul_f32_e32 v90, v11, v50
	v_mul_f32_e32 v91, v10, v50
	v_fma_f32 v90, v10, v66, -v90
	v_fma_f32 v91, v11, v66, v91
	global_store_dwordx2 v[32:33], v[90:91], off offset:48
	v_mul_f32_e32 v92, v11, v51
	v_mul_f32_e32 v93, v10, v51
	v_fma_f32 v92, v10, v67, -v92
	v_fma_f32 v93, v11, v67, v93
	global_store_dwordx2 v[32:33], v[92:93], off offset:56
	v_mul_f32_e32 v86, v11, v52
	v_mul_f32_e32 v87, v10, v52
	v_fma_f32 v86, v10, v68, -v86
	v_fma_f32 v87, v11, v68, v87
	global_store_dwordx2 v[32:33], v[86:87], off offset:64
	v_mul_f32_e32 v88, v11, v53
	v_mul_f32_e32 v89, v10, v53
	v_fma_f32 v88, v10, v69, -v88
	v_fma_f32 v89, v11, v69, v89
	global_store_dwordx2 v[32:33], v[88:89], off offset:72
	v_mul_f32_e32 v90, v11, v54
	v_mul_f32_e32 v91, v10, v54
	v_fma_f32 v90, v10, v70, -v90
	v_fma_f32 v91, v11, v70, v91
	global_store_dwordx2 v[32:33], v[90:91], off offset:80
	v_mul_f32_e32 v92, v11, v55
	v_mul_f32_e32 v93, v10, v55
	v_fma_f32 v92, v10, v71, -v92
	v_fma_f32 v93, v11, v71, v93
	global_store_dwordx2 v[32:33], v[92:93], off offset:88
	v_mul_f32_e32 v86, v11, v56
	v_mul_f32_e32 v87, v10, v56
	v_fma_f32 v86, v10, v72, -v86
	v_fma_f32 v87, v11, v72, v87
	global_store_dwordx2 v[32:33], v[86:87], off offset:96
	v_mul_f32_e32 v88, v11, v57
	v_mul_f32_e32 v89, v10, v57
	v_fma_f32 v88, v10, v73, -v88
	v_fma_f32 v89, v11, v73, v89
	global_store_dwordx2 v[32:33], v[88:89], off offset:104
	v_mul_f32_e32 v90, v11, v58
	v_mul_f32_e32 v91, v10, v58
	v_fma_f32 v90, v10, v74, -v90
	v_fma_f32 v91, v11, v74, v91
	global_store_dwordx2 v[32:33], v[90:91], off offset:112
	v_mul_f32_e32 v92, v11, v59
	v_mul_f32_e32 v93, v10, v59
	v_fma_f32 v92, v10, v75, -v92
	v_fma_f32 v93, v11, v75, v93
	global_store_dwordx2 v[32:33], v[92:93], off offset:120
	s_andn2_b64 exec, exec, s[6:7]
	s_cbranch_execnz .LBB0_691
